# mode0 attn: softmax exp/add stream re-spread evenly over all 24 MFMA gaps (in-place exps, single row-sum accumulator, bf16 packs as early as the P operand frees up)
# speedup vs baseline: 1.0166x; 1.0058x over previous
.LBB0_985:
	s_waitcnt lgkmcnt(3)
	v_mfma_f32_32x32x16_bf16 v[50:65], v[158:161], v[142:145], v[50:65]
	s_add_i32 s52, s73, s75
	s_add_i32 s0, s75, 0xffffff80
	s_add_i32 s37, s52, 0xffffff80
	s_cmp_lt_i32 s0, s70
	s_cselect_b64 s[6:7], -1, 0
	s_sub_i32 s0, s52, 64
	s_cmpk_gt_i32 s0, 0xff66
	s_cselect_b64 s[0:1], -1, 0
	s_add_i32 s36, s52, 0xffffffa1
	s_cmpk_gt_i32 s36, 0x5a
	s_cselect_b64 s[4:5], -1, 0
	s_cmp_gt_u32 s76, 1
	s_cselect_b32 s53, s74, s77
	s_mulk_i32 s53, 0x5000
	s_cmpk_gt_i32 s37, 0xff66
	v_add_u32_e32 v180, s53, v192
	s_cselect_b64 s[78:79], -1, 0
	v_add_u32_e32 v199, 0xc800, v180
	s_and_b64 s[6:7], s[78:79], s[6:7]
	ds_read_b64_tr_b16 v[200:201], v180 offset:56320
	ds_read_b64_tr_b16 v[202:203], v180 offset:58880
	s_mul_i32 s78, s72, 0x5000
	s_add_i32 s37, s78, 0
	v_mov_b32_e32 v224, 0
	v_exp_f32_e32 v98, v98
	v_exp_f32_e32 v99, v99
	v_add_f32_e32 v224, v98, v224
	v_add_f32_e32 v224, v99, v224
	s_waitcnt lgkmcnt(4)
	v_mfma_f32_32x32x16_bf16 v[34:49], v[154:157], v[142:145], v[34:49]
	ds_read_b64_tr_b16 v[204:205], v180 offset:56384
	ds_read_b64_tr_b16 v[206:207], v180 offset:58944
	global_load_dwordx4 v[162:165], v168, s[84:85] offset:1024
	global_load_dwordx4 v[158:161], v170, s[84:85] offset:1024
	v_exp_f32_e32 v100, v100
	s_waitcnt lgkmcnt(5)
	v_mfma_f32_32x32x16_bf16 v[18:33], v[150:153], v[142:145], v[18:33]
	ds_read_b64_tr_b16 v[208:209], v180 offset:56448
	ds_read_b64_tr_b16 v[210:211], v180 offset:59008
	global_load_dwordx4 v[150:153], v168, s[98:99] offset:2048
	global_load_dwordx4 v[154:157], v170, s[98:99] offset:2048
	v_add_f32_e32 v224, v100, v224
	v_exp_f32_e32 v101, v101
	v_exp_f32_e32 v102, v102
	v_add_f32_e32 v224, v101, v224
	v_add_f32_e32 v224, v102, v224
	s_waitcnt lgkmcnt(6)
	v_mfma_f32_32x32x16_bf16 v[2:17], v[146:149], v[142:145], v[2:17]
	ds_read_b64_tr_b16 v[220:221], v180 offset:56512
	ds_read_b64_tr_b16 v[222:223], v180 offset:59072
	v_exp_f32_e32 v103, v103
	s_waitcnt lgkmcnt(6)
	v_mfma_f32_32x32x16_bf16 v[50:65], v[200:203], v[138:141], v[50:65]
	ds_read_b64_tr_b16 v[146:147], v180 offset:61440
	ds_read_b64_tr_b16 v[148:149], v180 offset:64000
	v_add_f32_e32 v224, v103, v224
	v_exp_f32_e32 v104, v104
	v_cvt_pk_bf16_f32 v142, v98, v99
	v_add_f32_e32 v224, v104, v224
	v_cvt_pk_bf16_f32 v143, v100, v101
	v_cvt_pk_bf16_f32 v144, v102, v103
	s_waitcnt lgkmcnt(6)
	v_mfma_f32_32x32x16_bf16 v[34:49], v[204:207], v[138:141], v[34:49]
	ds_read_b64_tr_b16 v[200:201], v180 offset:61504
	ds_read_b64_tr_b16 v[202:203], v180 offset:64064
	v_exp_f32_e32 v105, v105
	v_exp_f32_e32 v106, v106
	v_add_f32_e32 v224, v105, v224
	v_add_f32_e32 v224, v106, v224
	v_cvt_pk_bf16_f32 v145, v104, v105
	s_waitcnt lgkmcnt(6)
	v_mfma_f32_32x32x16_bf16 v[18:33], v[208:211], v[138:141], v[18:33]
	ds_read_b64_tr_b16 v[98:99], v180 offset:61568
	ds_read_b64_tr_b16 v[100:101], v180 offset:64128
	v_exp_f32_e32 v107, v107
	s_waitcnt lgkmcnt(6)
	v_mfma_f32_32x32x16_bf16 v[2:17], v[220:223], v[138:141], v[2:17]
	ds_read_b64_tr_b16 v[204:205], v180 offset:61632
	ds_read_b64_tr_b16 v[206:207], v180 offset:64192
	v_add_f32_e32 v224, v107, v224
	v_exp_f32_e32 v108, v108
	v_exp_f32_e32 v109, v109
	v_add_f32_e32 v224, v108, v224
	v_add_f32_e32 v224, v109, v224
	s_waitcnt lgkmcnt(6)
	v_mfma_f32_32x32x16_bf16 v[50:65], v[146:149], v[134:137], v[50:65]
	ds_read_b64_tr_b16 v[208:209], v199 offset:15360
	ds_read_b64_tr_b16 v[210:211], v199 offset:17920
	v_exp_f32_e32 v110, v110
	v_cvt_pk_bf16_f32 v138, v106, v107
	v_add_f32_e32 v224, v110, v224
	v_cvt_pk_bf16_f32 v139, v108, v109
	s_waitcnt lgkmcnt(6)
	v_mfma_f32_32x32x16_bf16 v[34:49], v[200:203], v[134:137], v[34:49]
	ds_read_b64_tr_b16 v[102:103], v199 offset:15424
	ds_read_b64_tr_b16 v[104:105], v199 offset:17984
	v_exp_f32_e32 v111, v111
	s_waitcnt lgkmcnt(6)
	v_mfma_f32_32x32x16_bf16 v[18:33], v[98:101], v[134:137], v[18:33]
	ds_read_b64_tr_b16 v[146:147], v199 offset:15488
	ds_read_b64_tr_b16 v[148:149], v199 offset:18048
	v_add_f32_e32 v224, v111, v224
	v_cvt_pk_bf16_f32 v140, v110, v111
	v_exp_f32_e32 v112, v112
	v_exp_f32_e32 v113, v113
	v_add_f32_e32 v224, v112, v224
	v_add_f32_e32 v224, v113, v224
	v_cvt_pk_bf16_f32 v141, v112, v113
	s_waitcnt lgkmcnt(6)
	v_mfma_f32_32x32x16_bf16 v[2:17], v[204:207], v[134:137], v[2:17]
	ds_read_b64_tr_b16 v[98:99], v199 offset:15552
	ds_read_b64_tr_b16 v[100:101], v199 offset:18112
	v_exp_f32_e32 v66, v66
	s_waitcnt lgkmcnt(6)
	v_mfma_f32_32x32x16_bf16 v[50:65], v[208:211], v[130:133], v[50:65]
	ds_read_b128 v[200:203], v196
	v_add_f32_e32 v224, v66, v224
	v_exp_f32_e32 v67, v67
	v_exp_f32_e32 v68, v68
	v_add_f32_e32 v224, v67, v224
	v_add_f32_e32 v224, v68, v224
	v_cvt_pk_bf16_f32 v134, v66, v67
	s_waitcnt lgkmcnt(5)
	v_mfma_f32_32x32x16_bf16 v[34:49], v[102:105], v[130:133], v[34:49]
	ds_read_b128 v[204:207], v196 offset:8704
	v_exp_f32_e32 v69, v69
	s_waitcnt lgkmcnt(4)
	v_mfma_f32_32x32x16_bf16 v[18:33], v[146:149], v[130:133], v[18:33]
	ds_read_b128 v[208:211], v196 offset:32
	v_add_f32_e32 v224, v69, v224
	v_cvt_pk_bf16_f32 v135, v68, v69
	v_exp_f32_e32 v70, v70
	s_waitcnt lgkmcnt(3)
	v_mfma_f32_32x32x16_bf16 v[2:17], v[98:101], v[130:133], v[2:17]
	ds_read_b128 v[146:149], v196 offset:8736
	ds_read_b128 v[66:69], v196 offset:64
	v_add_f32_e32 v224, v70, v224
	v_exp_f32_e32 v71, v71
	v_exp_f32_e32 v72, v72
	v_add_f32_e32 v224, v71, v224
	v_add_f32_e32 v224, v72, v224
	v_cvt_pk_bf16_f32 v136, v70, v71
	s_waitcnt lgkmcnt(4)
	v_mfma_f32_32x32x16_bf16 v[98:113], v[200:203], v[114:117], v[228:243]
	v_exp_f32_e32 v73, v73
	s_waitcnt lgkmcnt(3)
	v_mfma_f32_32x32x16_bf16 v[82:97], v[204:207], v[114:117], v[228:243]
	ds_read_b128 v[200:203], v196 offset:8768
	v_add_f32_e32 v224, v73, v224
	v_cvt_pk_bf16_f32 v137, v72, v73
	v_exp_f32_e32 v74, v74
	v_exp_f32_e32 v75, v75
	v_add_f32_e32 v224, v74, v224
	v_add_f32_e32 v224, v75, v224
	v_cvt_pk_bf16_f32 v130, v74, v75
	s_waitcnt lgkmcnt(3)
	v_mfma_f32_32x32x16_bf16 v[98:113], v[208:211], v[118:121], v[98:113]
	ds_read_b128 v[204:207], v196 offset:96
	v_exp_f32_e32 v76, v76
	s_waitcnt lgkmcnt(3)
	v_mfma_f32_32x32x16_bf16 v[82:97], v[146:149], v[118:121], v[82:97]
	ds_read_b128 v[70:73], v196 offset:8800
	v_add_f32_e32 v224, v76, v224
	v_exp_f32_e32 v77, v77
	s_waitcnt lgkmcnt(3)
	v_mfma_f32_32x32x16_bf16 v[98:113], v[66:69], v[122:125], v[98:113]
	s_waitcnt vmcnt(3)
	ds_write_b128 v190, v[162:165] offset:25600
	s_waitcnt vmcnt(2)
	ds_write_b128 v188, v[158:161] offset:25600
	v_add_f32_e32 v224, v77, v224
	v_cvt_pk_bf16_f32 v131, v76, v77
	v_exp_f32_e32 v78, v78
	v_exp_f32_e32 v79, v79
	v_add_f32_e32 v224, v78, v224
	v_add_f32_e32 v224, v79, v224
	v_cvt_pk_bf16_f32 v132, v78, v79
	s_waitcnt lgkmcnt(4)
	v_mfma_f32_32x32x16_bf16 v[82:97], v[200:203], v[122:125], v[82:97]
	v_exp_f32_e32 v80, v80
	s_waitcnt lgkmcnt(3)
	v_mfma_f32_32x32x16_bf16 v[98:113], v[204:207], v[126:129], v[98:113]
	v_add_u32_e32 v68, s37, v176
	s_waitcnt vmcnt(1)
	ds_write_b128 v68, v[150:153] offset:51200
	v_add_u32_e32 v68, s37, v178
	s_waitcnt vmcnt(0)
	ds_write_b128 v68, v[154:157] offset:51200
	s_cmpk_lt_u32 s76, 0x7f
	s_cselect_b32 s84, 0x4d000, 0
	s_add_u32 s84, s84, s88
	s_add_u32 s84, s8, s84
	s_addc_u32 s85, s9, 0
	s_add_u32 s98, s8, s88
	s_addc_u32 s99, s9, 0
	v_add_f32_e32 v224, v80, v224
	v_exp_f32_e32 v81, v81
	s_waitcnt lgkmcnt(4)
	v_mfma_f32_32x32x16_bf16 v[82:97], v[70:73], v[126:129], v[82:97]
	v_add_f32_e32 v199, v81, v224
	v_cvt_pk_bf16_f32 v133, v80, v81
	s_mul_i32 s37, s77, 0x5000
	v_add_u32_e32 v201, s37, v192
	ds_read_b64_tr_b16 v[158:159], v201 offset:51200
	ds_read_b64_tr_b16 v[154:155], v201 offset:51264
	ds_read_b64_tr_b16 v[150:151], v201 offset:51328
	ds_read_b64_tr_b16 v[146:147], v201 offset:51392
	ds_read_b64_tr_b16 v[160:161], v201 offset:53760
	ds_read_b64_tr_b16 v[156:157], v201 offset:53824
	ds_read_b64_tr_b16 v[152:153], v201 offset:53888
	ds_read_b64_tr_b16 v[148:149], v201 offset:53952
	s_andn2_b64 vcc, exec, s[6:7]
	v_add_u32_e32 v200, s75, v179
	s_cbranch_vccnz .LBB0_987
	v_add_u32_e32 v66, 0x80, v200
	v_med3_i32 v67, v66, 0, v216
	v_med3_i32 v66, v66, s46, v217
	v_lshl_add_u32 v68, v66, 2, s15
	v_add_u32_e32 v66, 0x81, v200
	v_med3_i32 v69, v66, 0, v216
	v_med3_i32 v66, v66, s46, v217
	v_lshl_add_u32 v70, v66, 2, s15
	v_add_u32_e32 v66, 0x82, v200
	v_med3_i32 v71, v66, 0, v216
	v_med3_i32 v66, v66, s46, v217
	v_lshl_add_u32 v72, v66, 2, s15
	v_add_u32_e32 v66, 0x83, v200
	v_med3_i32 v73, v66, 0, v216
	v_med3_i32 v66, v66, s46, v217
	v_lshl_add_u32 v67, v67, 2, s15
	v_lshl_add_u32 v69, v69, 2, s15
	v_lshl_add_u32 v71, v71, 2, s15
	v_lshl_add_u32 v73, v73, 2, s15
	v_lshl_add_u32 v74, v66, 2, s15
	ds_read_b32 v66, v67
	ds_read_b32 v68, v68 offset:128
	ds_read_b32 v67, v69
	ds_read_b32 v69, v70 offset:128
	ds_read_b32 v70, v71
	ds_read_b32 v72, v72 offset:128
	ds_read_b32 v71, v73
	ds_read_b32 v73, v74 offset:128
	v_add_u32_e32 v74, 0x88, v200
	v_med3_i32 v75, v74, 0, v216
	v_med3_i32 v74, v74, s46, v217
	v_lshl_add_u32 v76, v74, 2, s15
	v_add_u32_e32 v74, 0x89, v200
	v_med3_i32 v77, v74, 0, v216
	v_med3_i32 v74, v74, s46, v217
	v_lshl_add_u32 v78, v74, 2, s15
	v_add_u32_e32 v74, 0x8a, v200
	v_med3_i32 v79, v74, 0, v216
	v_med3_i32 v74, v74, s46, v217
	v_lshl_add_u32 v80, v74, 2, s15
	v_add_u32_e32 v74, 0x8b, v200
	v_med3_i32 v81, v74, 0, v216
	v_med3_i32 v74, v74, s46, v217
	v_lshl_add_u32 v75, v75, 2, s15
	v_lshl_add_u32 v77, v77, 2, s15
	v_lshl_add_u32 v79, v79, 2, s15
	v_lshl_add_u32 v81, v81, 2, s15
	v_lshl_add_u32 v162, v74, 2, s15
	ds_read_b32 v74, v75
	ds_read_b32 v76, v76 offset:128
	ds_read_b32 v75, v77
	ds_read_b32 v77, v78 offset:128
	ds_read_b32 v78, v79
	ds_read_b32 v80, v80 offset:128
	ds_read_b32 v79, v81
	ds_read_b32 v81, v162 offset:128
	v_add_u32_e32 v162, 0x90, v200
	v_med3_i32 v163, v162, 0, v216
	v_med3_i32 v162, v162, s46, v217
	v_lshl_add_u32 v164, v162, 2, s15
	v_add_u32_e32 v162, 0x91, v200
	v_med3_i32 v165, v162, 0, v216
	v_med3_i32 v162, v162, s46, v217
	v_lshl_add_u32 v180, v162, 2, s15
	v_add_u32_e32 v162, 0x92, v200
	v_med3_i32 v202, v162, 0, v216
	v_med3_i32 v162, v162, s46, v217
	v_add_u32_e32 v207, 0x99, v200
	v_lshl_add_u32 v203, v162, 2, s15
	v_add_u32_e32 v162, 0x93, v200
	v_med3_i32 v208, v207, 0, v216
	v_med3_i32 v207, v207, s46, v217
	v_med3_i32 v204, v162, 0, v216
	v_lshl_add_u32 v214, v207, 2, s15
	v_add_u32_e32 v207, 0x9a, v200
	v_lshl_add_u32 v163, v163, 2, s15
	v_lshl_add_u32 v165, v165, 2, s15
	v_lshl_add_u32 v202, v202, 2, s15
	v_med3_i32 v162, v162, s46, v217
	v_lshl_add_u32 v205, v204, 2, s15
	v_lshl_add_u32 v209, v208, 2, s15
	v_med3_i32 v208, v207, 0, v216
	v_med3_i32 v207, v207, s46, v217
	v_lshl_add_u32 v206, v162, 2, s15
	ds_read_b32 v162, v163
	ds_read_b32 v164, v164 offset:128
	ds_read_b32 v163, v165
	ds_read_b32 v165, v180 offset:128
	ds_read_b32 v202, v202
	ds_read_b32 v204, v203 offset:128
	ds_read_b32 v203, v205
	ds_read_b32 v205, v206 offset:128
	v_add_u32_e32 v180, 0x98, v200
	v_lshl_add_u32 v212, v207, 2, s15
	v_add_u32_e32 v207, 0x9b, v200
	v_med3_i32 v206, v180, 0, v216
	v_lshl_add_u32 v210, v208, 2, s15
	v_med3_i32 v208, v207, 0, v216
	v_med3_i32 v207, v207, s46, v217
	v_med3_i32 v180, v180, s46, v217
	v_lshl_add_u32 v206, v206, 2, s15
	v_lshl_add_u32 v211, v208, 2, s15
	v_lshl_add_u32 v213, v207, 2, s15
	v_lshl_add_u32 v180, v180, 2, s15
	ds_read_b32 v206, v206
	ds_read_b32 v208, v180 offset:128
	ds_read_b32 v210, v210
	ds_read_b32 v211, v211
	ds_read_b32 v207, v209
	ds_read_b32 v213, v213 offset:128
	ds_read_b32 v212, v212 offset:128
	ds_read_b32 v209, v214 offset:128
	s_waitcnt lgkmcnt(4)
	v_pk_add_f32 v[112:113], v[112:113], v[210:211]
	s_waitcnt lgkmcnt(3)
	v_pk_add_f32 v[110:111], v[110:111], v[206:207]
	v_pk_add_f32 v[108:109], v[108:109], v[202:203]
	v_pk_add_f32 v[106:107], v[106:107], v[162:163]
	v_pk_add_f32 v[104:105], v[104:105], v[78:79]
	v_pk_add_f32 v[102:103], v[102:103], v[74:75]
	v_pk_add_f32 v[100:101], v[100:101], v[70:71]
	v_pk_add_f32 v[98:99], v[98:99], v[66:67]
	s_waitcnt lgkmcnt(1)
	v_pk_add_f32 v[96:97], v[96:97], v[212:213]
	s_waitcnt lgkmcnt(0)
	v_pk_add_f32 v[94:95], v[94:95], v[208:209]
	v_pk_add_f32 v[92:93], v[92:93], v[204:205]
	v_pk_add_f32 v[90:91], v[90:91], v[164:165]
	v_pk_add_f32 v[88:89], v[88:89], v[80:81]
	v_pk_add_f32 v[86:87], v[86:87], v[76:77]
	v_pk_add_f32 v[84:85], v[84:85], v[72:73]
	v_pk_add_f32 v[82:83], v[82:83], v[68:69]

.LBB0_992:
	v_mfma_f32_32x32x16_bf16 v[50:65], v[158:161], v[142:145], v[50:65]
	s_cmpk_lt_i32 s36, 0x5b
	s_cselect_b64 s[36:37], -1, 0
	s_add_i32 s6, s75, 0xffffff40
	s_addk_i32 s52, 0xff40
	s_cmpk_lt_i32 s52, 0xfea7
	s_cselect_b64 s[4:5], -1, 0
	s_cmp_gt_i32 s6, s71
	s_cselect_b64 s[6:7], -1, 0
	v_add_u32_e32 v210, 0xc800, v201
	s_cmpk_gt_u32 s76, 0x7e
	s_cselect_b64 s[52:53], -1, 0
	ds_read_b64_tr_b16 v[202:203], v201 offset:56320
	ds_read_b64_tr_b16 v[204:205], v201 offset:58880
	s_mul_i32 s79, s74, 0x5000
	s_add_i32 s79, s79, 0
	v_mov_b32_e32 v224, 0
	v_exp_f32_e32 v98, v98
	v_exp_f32_e32 v99, v99
	v_add_f32_e32 v224, v98, v224
	v_add_f32_e32 v224, v99, v224
	v_mfma_f32_32x32x16_bf16 v[34:49], v[154:157], v[142:145], v[34:49]
	ds_read_b64_tr_b16 v[206:207], v201 offset:56384
	ds_read_b64_tr_b16 v[208:209], v201 offset:58944
	ds_read_b64_tr_b16 v[220:221], v201 offset:56448
	ds_read_b64_tr_b16 v[222:223], v201 offset:59008
	global_load_dwordx4 v[162:165], v168, s[84:85] offset:1024
	global_load_dwordx4 v[158:161], v170, s[84:85] offset:1024
	v_exp_f32_e32 v100, v100
	v_mfma_f32_32x32x16_bf16 v[18:33], v[150:153], v[142:145], v[18:33]
	global_load_dwordx4 v[150:153], v168, s[98:99] offset:2048
	global_load_dwordx4 v[154:157], v170, s[98:99] offset:2048
	v_add_f32_e32 v224, v100, v224
	v_exp_f32_e32 v101, v101
	v_exp_f32_e32 v102, v102
	v_add_f32_e32 v224, v101, v224
	v_add_f32_e32 v224, v102, v224
	v_mfma_f32_32x32x16_bf16 v[2:17], v[146:149], v[142:145], v[2:17]
	ds_read_b64_tr_b16 v[182:183], v201 offset:56512
	ds_read_b64_tr_b16 v[184:185], v201 offset:59072
	v_exp_f32_e32 v103, v103
	s_waitcnt lgkmcnt(6)
	v_mfma_f32_32x32x16_bf16 v[50:65], v[202:205], v[138:141], v[50:65]
	ds_read_b64_tr_b16 v[146:147], v201 offset:61440
	ds_read_b64_tr_b16 v[148:149], v201 offset:64000
	v_add_f32_e32 v224, v103, v224
	v_exp_f32_e32 v104, v104
	v_cvt_pk_bf16_f32 v142, v98, v99
	v_add_f32_e32 v224, v104, v224
	v_cvt_pk_bf16_f32 v143, v100, v101
	v_cvt_pk_bf16_f32 v144, v102, v103
	s_waitcnt lgkmcnt(6)
	v_mfma_f32_32x32x16_bf16 v[34:49], v[206:209], v[138:141], v[34:49]
	ds_read_b64_tr_b16 v[202:203], v201 offset:61504
	ds_read_b64_tr_b16 v[204:205], v201 offset:64064
	v_exp_f32_e32 v105, v105
	v_exp_f32_e32 v106, v106
	v_add_f32_e32 v224, v105, v224
	v_add_f32_e32 v224, v106, v224
	v_cvt_pk_bf16_f32 v145, v104, v105
	s_waitcnt lgkmcnt(6)
	v_mfma_f32_32x32x16_bf16 v[18:33], v[220:223], v[138:141], v[18:33]
	ds_read_b64_tr_b16 v[98:99], v201 offset:61568
	ds_read_b64_tr_b16 v[100:101], v201 offset:64128
	v_exp_f32_e32 v107, v107
	s_waitcnt lgkmcnt(6)
	v_mfma_f32_32x32x16_bf16 v[2:17], v[182:185], v[138:141], v[2:17]
	ds_read_b64_tr_b16 v[206:207], v201 offset:61632
	ds_read_b64_tr_b16 v[208:209], v201 offset:64192
	v_add_f32_e32 v224, v107, v224
	v_exp_f32_e32 v108, v108
	v_exp_f32_e32 v109, v109
	v_add_f32_e32 v224, v108, v224
	v_add_f32_e32 v224, v109, v224
	s_waitcnt lgkmcnt(6)
	v_mfma_f32_32x32x16_bf16 v[50:65], v[146:149], v[134:137], v[50:65]
	ds_read_b64_tr_b16 v[182:183], v210 offset:15360
	ds_read_b64_tr_b16 v[184:185], v210 offset:17920
	v_exp_f32_e32 v110, v110
	v_cvt_pk_bf16_f32 v138, v106, v107
	v_add_f32_e32 v224, v110, v224
	v_cvt_pk_bf16_f32 v139, v108, v109
	s_waitcnt lgkmcnt(6)
	v_mfma_f32_32x32x16_bf16 v[34:49], v[202:205], v[134:137], v[34:49]
	ds_read_b64_tr_b16 v[102:103], v210 offset:15424
	ds_read_b64_tr_b16 v[104:105], v210 offset:17984
	v_exp_f32_e32 v111, v111
	s_waitcnt lgkmcnt(6)
	v_mfma_f32_32x32x16_bf16 v[18:33], v[98:101], v[134:137], v[18:33]
	ds_read_b64_tr_b16 v[146:147], v210 offset:15488
	ds_read_b64_tr_b16 v[148:149], v210 offset:18048
	v_add_f32_e32 v224, v111, v224
	v_cvt_pk_bf16_f32 v140, v110, v111
	v_exp_f32_e32 v112, v112
	v_exp_f32_e32 v113, v113
	v_add_f32_e32 v224, v112, v224
	v_add_f32_e32 v224, v113, v224
	v_cvt_pk_bf16_f32 v141, v112, v113
	s_waitcnt lgkmcnt(6)
	v_mfma_f32_32x32x16_bf16 v[2:17], v[206:209], v[134:137], v[2:17]
	ds_read_b64_tr_b16 v[98:99], v210 offset:15552
	ds_read_b64_tr_b16 v[100:101], v210 offset:18112
	v_exp_f32_e32 v82, v82
	s_waitcnt lgkmcnt(6)
	v_mfma_f32_32x32x16_bf16 v[50:65], v[182:185], v[130:133], v[50:65]
	ds_read_b128 v[202:205], v196 offset:25600
	v_add_f32_e32 v224, v82, v224
	v_exp_f32_e32 v83, v83
	v_exp_f32_e32 v84, v84
	v_add_f32_e32 v224, v83, v224
	v_add_f32_e32 v224, v84, v224
	v_cvt_pk_bf16_f32 v134, v82, v83
	s_waitcnt lgkmcnt(5)
	v_mfma_f32_32x32x16_bf16 v[34:49], v[102:105], v[130:133], v[34:49]
	ds_read_b128 v[182:185], v196 offset:34304
	v_exp_f32_e32 v85, v85
	s_waitcnt lgkmcnt(4)
	v_mfma_f32_32x32x16_bf16 v[18:33], v[146:149], v[130:133], v[18:33]
	ds_read_b128 v[206:209], v196 offset:25632
	v_add_f32_e32 v224, v85, v224
	v_cvt_pk_bf16_f32 v135, v84, v85
	v_exp_f32_e32 v86, v86
	s_waitcnt lgkmcnt(3)
	v_mfma_f32_32x32x16_bf16 v[2:17], v[98:101], v[130:133], v[2:17]
	ds_read_b128 v[146:149], v196 offset:34336
	ds_read_b128 v[82:85], v196 offset:25664
	v_add_f32_e32 v224, v86, v224
	v_exp_f32_e32 v87, v87
	v_exp_f32_e32 v88, v88
	v_add_f32_e32 v224, v87, v224
	v_add_f32_e32 v224, v88, v224
	v_cvt_pk_bf16_f32 v136, v86, v87
	s_waitcnt lgkmcnt(4)
	v_mfma_f32_32x32x16_bf16 v[98:113], v[202:205], v[114:117], v[228:243]
	v_exp_f32_e32 v89, v89
	s_waitcnt lgkmcnt(3)
	v_mfma_f32_32x32x16_bf16 v[66:81], v[182:185], v[114:117], v[228:243]
	ds_read_b128 v[202:205], v196 offset:34368
	v_add_f32_e32 v224, v89, v224
	v_cvt_pk_bf16_f32 v137, v88, v89
	v_exp_f32_e32 v90, v90
	v_exp_f32_e32 v91, v91
	v_add_f32_e32 v224, v90, v224
	v_add_f32_e32 v224, v91, v224
	v_cvt_pk_bf16_f32 v130, v90, v91
	s_waitcnt lgkmcnt(3)
	v_mfma_f32_32x32x16_bf16 v[98:113], v[206:209], v[118:121], v[98:113]
	ds_read_b128 v[182:185], v196 offset:25696
	v_exp_f32_e32 v92, v92
	s_waitcnt lgkmcnt(3)
	v_mfma_f32_32x32x16_bf16 v[66:81], v[146:149], v[118:121], v[66:81]
	ds_read_b128 v[86:89], v196 offset:34400
	v_add_f32_e32 v224, v92, v224
	v_exp_f32_e32 v93, v93
	s_waitcnt lgkmcnt(3)
	v_mfma_f32_32x32x16_bf16 v[98:113], v[82:85], v[122:125], v[98:113]
	s_waitcnt vmcnt(3)
	ds_write_b128 v190, v[162:165]
	s_waitcnt vmcnt(2)
	ds_write_b128 v188, v[158:161]
	v_add_f32_e32 v224, v93, v224
	v_cvt_pk_bf16_f32 v131, v92, v93
	v_exp_f32_e32 v94, v94
	v_exp_f32_e32 v95, v95
	v_add_f32_e32 v224, v94, v224
	v_add_f32_e32 v224, v95, v224
	v_cvt_pk_bf16_f32 v132, v94, v95
	s_waitcnt lgkmcnt(4)
	v_mfma_f32_32x32x16_bf16 v[66:81], v[202:205], v[122:125], v[66:81]
	v_exp_f32_e32 v96, v96
	s_waitcnt lgkmcnt(3)
	v_mfma_f32_32x32x16_bf16 v[98:113], v[182:185], v[126:129], v[98:113]
	v_add_u32_e32 v84, s79, v176
	s_waitcnt vmcnt(1)
	ds_write_b128 v84, v[150:153] offset:51200
	v_add_u32_e32 v84, s79, v178
	s_waitcnt vmcnt(0)
	ds_write_b128 v84, v[154:157] offset:51200
	s_cmpk_lt_u32 s76, 0x7f
	s_cselect_b32 s84, s67, 0
	s_cselect_b32 s98, 0x4d000, 0
	s_add_u32 s84, s84, s88
	s_add_u32 s98, s98, s88
	s_add_u32 s84, s8, s84
	s_addc_u32 s85, s9, 0
	s_add_u32 s98, s8, s98
	s_addc_u32 s99, s9, 0
	v_add_f32_e32 v224, v96, v224
	v_exp_f32_e32 v97, v97
	s_waitcnt lgkmcnt(4)
	v_mfma_f32_32x32x16_bf16 v[66:81], v[86:89], v[126:129], v[66:81]
	v_add_f32_e32 v163, v97, v224
	v_cvt_pk_bf16_f32 v133, v96, v97
	v_add_u32_e32 v82, s78, v192
	ds_read_b64_tr_b16 v[158:159], v82 offset:51200
	ds_read_b64_tr_b16 v[154:155], v82 offset:51264
	ds_read_b64_tr_b16 v[150:151], v82 offset:51328
	ds_read_b64_tr_b16 v[146:147], v82 offset:51392
	ds_read_b64_tr_b16 v[160:161], v82 offset:53760
	ds_read_b64_tr_b16 v[156:157], v82 offset:53824
	ds_read_b64_tr_b16 v[152:153], v82 offset:53888
	ds_read_b64_tr_b16 v[148:149], v82 offset:53952
	s_and_b64 s[0:1], s[0:1], s[36:37]
	s_andn2_b64 vcc, exec, s[0:1]
	s_cbranch_vccnz .LBB0_994
	v_add_u32_e32 v82, 0xc0, v200
	v_med3_i32 v83, v82, 0, v216
	v_med3_i32 v82, v82, s46, v217
	v_lshl_add_u32 v84, v82, 2, s15
	v_add_u32_e32 v82, 0xc1, v200
	v_med3_i32 v85, v82, 0, v216
	v_med3_i32 v82, v82, s46, v217
	v_lshl_add_u32 v86, v82, 2, s15
	v_add_u32_e32 v82, 0xc2, v200
	v_med3_i32 v87, v82, 0, v216
	v_med3_i32 v82, v82, s46, v217
	v_lshl_add_u32 v88, v82, 2, s15
	v_add_u32_e32 v82, 0xc3, v200
	v_med3_i32 v89, v82, 0, v216
	v_med3_i32 v82, v82, s46, v217
	v_lshl_add_u32 v83, v83, 2, s15
	v_lshl_add_u32 v85, v85, 2, s15
	v_lshl_add_u32 v87, v87, 2, s15
	v_lshl_add_u32 v89, v89, 2, s15
	v_lshl_add_u32 v90, v82, 2, s15
	ds_read_b32 v82, v83
	ds_read_b32 v84, v84 offset:128
	ds_read_b32 v83, v85
	ds_read_b32 v85, v86 offset:128
	ds_read_b32 v86, v87
	ds_read_b32 v88, v88 offset:128
	ds_read_b32 v87, v89
	ds_read_b32 v89, v90 offset:128
	v_add_u32_e32 v90, 0xc8, v200
	v_med3_i32 v91, v90, 0, v216
	v_med3_i32 v90, v90, s46, v217
	v_lshl_add_u32 v92, v90, 2, s15
	v_add_u32_e32 v90, 0xc9, v200
	v_med3_i32 v93, v90, 0, v216
	v_med3_i32 v90, v90, s46, v217
	v_lshl_add_u32 v94, v90, 2, s15
	v_add_u32_e32 v90, 0xca, v200
	v_med3_i32 v95, v90, 0, v216
	v_med3_i32 v90, v90, s46, v217
	v_add_u32_e32 v165, 0xd1, v200
	v_lshl_add_u32 v96, v90, 2, s15
	v_add_u32_e32 v90, 0xcb, v200
	v_med3_i32 v182, v165, 0, v216
	v_med3_i32 v165, v165, s46, v217
	v_med3_i32 v97, v90, 0, v216
	v_med3_i32 v90, v90, s46, v217
	v_lshl_add_u32 v184, v165, 2, s15
	v_add_u32_e32 v165, 0xd2, v200
	v_lshl_add_u32 v91, v91, 2, s15
	v_lshl_add_u32 v93, v93, 2, s15
	v_lshl_add_u32 v95, v95, 2, s15
	v_lshl_add_u32 v97, v97, 2, s15
	v_lshl_add_u32 v162, v90, 2, s15
	v_lshl_add_u32 v183, v182, 2, s15
	v_med3_i32 v182, v165, 0, v216
	v_med3_i32 v165, v165, s46, v217
	ds_read_b32 v90, v91
	ds_read_b32 v92, v92 offset:128
	ds_read_b32 v91, v93
	ds_read_b32 v93, v94 offset:128
	ds_read_b32 v94, v95
	ds_read_b32 v96, v96 offset:128
	ds_read_b32 v95, v97
	ds_read_b32 v97, v162 offset:128
	v_add_u32_e32 v162, 0xd0, v200
	v_lshl_add_u32 v201, v165, 2, s15
	v_add_u32_e32 v165, 0xd3, v200
	v_med3_i32 v164, v162, 0, v216
	v_lshl_add_u32 v185, v182, 2, s15
	v_med3_i32 v182, v165, 0, v216
	v_med3_i32 v165, v165, s46, v217
	v_med3_i32 v162, v162, s46, v217
	v_lshl_add_u32 v164, v164, 2, s15
	v_lshl_add_u32 v203, v182, 2, s15
	v_lshl_add_u32 v204, v165, 2, s15
	v_lshl_add_u32 v162, v162, 2, s15
	ds_read_b32 v164, v164
	ds_read_b32 v182, v162 offset:128
	ds_read_b32 v165, v183
	ds_read_b32 v183, v184 offset:128
	ds_read_b32 v184, v185
	ds_read_b32 v202, v201 offset:128
	ds_read_b32 v185, v203
	ds_read_b32 v203, v204 offset:128
	v_add_u32_e32 v204, 0xd9, v200
	v_med3_i32 v205, v204, 0, v216
	v_med3_i32 v204, v204, s46, v217
	v_lshl_add_u32 v210, v204, 2, s15
	v_add_u32_e32 v204, 0xda, v200
	v_add_u32_e32 v162, 0xd8, v200
	v_med3_i32 v206, v204, 0, v216
	v_med3_i32 v204, v204, s46, v217
	v_add_u32_e32 v200, 0xdb, v200
	v_med3_i32 v201, v162, 0, v216
	v_lshl_add_u32 v208, v204, 2, s15
	v_med3_i32 v204, v200, 0, v216
	v_med3_i32 v200, v200, s46, v217
	v_med3_i32 v162, v162, s46, v217
	v_lshl_add_u32 v201, v201, 2, s15
	v_lshl_add_u32 v205, v205, 2, s15
	v_lshl_add_u32 v206, v206, 2, s15
	v_lshl_add_u32 v207, v204, 2, s15
	v_lshl_add_u32 v209, v200, 2, s15
	v_lshl_add_u32 v162, v162, 2, s15
	ds_read_b32 v200, v201
	ds_read_b32 v204, v162 offset:128
	ds_read_b32 v206, v206
	ds_read_b32 v207, v207
	ds_read_b32 v201, v205
	ds_read_b32 v209, v209 offset:128
	ds_read_b32 v208, v208 offset:128
	ds_read_b32 v205, v210 offset:128
	s_waitcnt lgkmcnt(4)
	v_pk_add_f32 v[112:113], v[112:113], v[206:207]
	s_waitcnt lgkmcnt(3)
	v_pk_add_f32 v[110:111], v[110:111], v[200:201]
	v_pk_add_f32 v[108:109], v[108:109], v[184:185]
	v_pk_add_f32 v[106:107], v[106:107], v[164:165]
	v_pk_add_f32 v[104:105], v[104:105], v[94:95]
	v_pk_add_f32 v[102:103], v[102:103], v[90:91]
	v_pk_add_f32 v[100:101], v[100:101], v[86:87]
	v_pk_add_f32 v[98:99], v[98:99], v[82:83]
	s_waitcnt lgkmcnt(1)
	v_pk_add_f32 v[80:81], v[80:81], v[208:209]
	s_waitcnt lgkmcnt(0)
	v_pk_add_f32 v[78:79], v[78:79], v[204:205]
	v_pk_add_f32 v[76:77], v[76:77], v[202:203]
	v_pk_add_f32 v[74:75], v[74:75], v[182:183]
	v_pk_add_f32 v[72:73], v[72:73], v[96:97]
	v_pk_add_f32 v[70:71], v[70:71], v[92:93]
	v_pk_add_f32 v[68:69], v[68:69], v[88:89]
	v_pk_add_f32 v[66:67], v[66:67], v[84:85]
